# c24 + DIFF fast-path event block: the 32 re-reference subtractions packed as 16 v_pk_add_f32 (exposed VALU, no MFMA in flight)
# baseline (speedup 1.0000x reference)
.Lf_odd_resc:
	v_add_f32_e32 v246, 0x42200000, v245
	v_min_f32_e32 v246, 0x42f00000, v246
	v_max3_f32 v246, v246, v245, 0
	v_exp_f32_e64 v225, -v246
	v_add_f32_e32 v221, v221, v246
	v_pk_add_f32 v[128:129], v[128:129], v[246:247] op_sel_hi:[1,0] neg_lo:[0,1] neg_hi:[0,1]
	v_pk_add_f32 v[130:131], v[130:131], v[246:247] op_sel_hi:[1,0] neg_lo:[0,1] neg_hi:[0,1]
	v_pk_add_f32 v[132:133], v[132:133], v[246:247] op_sel_hi:[1,0] neg_lo:[0,1] neg_hi:[0,1]
	v_pk_add_f32 v[134:135], v[134:135], v[246:247] op_sel_hi:[1,0] neg_lo:[0,1] neg_hi:[0,1]
	v_pk_add_f32 v[136:137], v[136:137], v[246:247] op_sel_hi:[1,0] neg_lo:[0,1] neg_hi:[0,1]
	v_pk_add_f32 v[138:139], v[138:139], v[246:247] op_sel_hi:[1,0] neg_lo:[0,1] neg_hi:[0,1]
	v_pk_add_f32 v[140:141], v[140:141], v[246:247] op_sel_hi:[1,0] neg_lo:[0,1] neg_hi:[0,1]
	v_pk_add_f32 v[142:143], v[142:143], v[246:247] op_sel_hi:[1,0] neg_lo:[0,1] neg_hi:[0,1]
	v_pk_add_f32 v[112:113], v[112:113], v[246:247] op_sel_hi:[1,0] neg_lo:[0,1] neg_hi:[0,1]
	v_pk_add_f32 v[114:115], v[114:115], v[246:247] op_sel_hi:[1,0] neg_lo:[0,1] neg_hi:[0,1]
	v_pk_add_f32 v[116:117], v[116:117], v[246:247] op_sel_hi:[1,0] neg_lo:[0,1] neg_hi:[0,1]
	v_pk_add_f32 v[118:119], v[118:119], v[246:247] op_sel_hi:[1,0] neg_lo:[0,1] neg_hi:[0,1]
	v_pk_add_f32 v[120:121], v[120:121], v[246:247] op_sel_hi:[1,0] neg_lo:[0,1] neg_hi:[0,1]
	v_pk_add_f32 v[122:123], v[122:123], v[246:247] op_sel_hi:[1,0] neg_lo:[0,1] neg_hi:[0,1]
	v_pk_add_f32 v[124:125], v[124:125], v[246:247] op_sel_hi:[1,0] neg_lo:[0,1] neg_hi:[0,1]
	v_pk_add_f32 v[126:127], v[126:127], v[246:247] op_sel_hi:[1,0] neg_lo:[0,1] neg_hi:[0,1]
	s_branch .Lf_odd_exp

.Lf_even_resc:
	v_add_f32_e32 v246, 0x42200000, v245
	v_min_f32_e32 v246, 0x42f00000, v246
	v_max3_f32 v246, v246, v245, 0
	v_exp_f32_e64 v196, -v246
	v_add_f32_e32 v221, v221, v246
	v_pk_add_f32 v[128:129], v[128:129], v[246:247] op_sel_hi:[1,0] neg_lo:[0,1] neg_hi:[0,1]
	v_pk_add_f32 v[130:131], v[130:131], v[246:247] op_sel_hi:[1,0] neg_lo:[0,1] neg_hi:[0,1]
	v_pk_add_f32 v[132:133], v[132:133], v[246:247] op_sel_hi:[1,0] neg_lo:[0,1] neg_hi:[0,1]
	v_pk_add_f32 v[134:135], v[134:135], v[246:247] op_sel_hi:[1,0] neg_lo:[0,1] neg_hi:[0,1]
	v_pk_add_f32 v[136:137], v[136:137], v[246:247] op_sel_hi:[1,0] neg_lo:[0,1] neg_hi:[0,1]
	v_pk_add_f32 v[138:139], v[138:139], v[246:247] op_sel_hi:[1,0] neg_lo:[0,1] neg_hi:[0,1]
	v_pk_add_f32 v[140:141], v[140:141], v[246:247] op_sel_hi:[1,0] neg_lo:[0,1] neg_hi:[0,1]
	v_pk_add_f32 v[142:143], v[142:143], v[246:247] op_sel_hi:[1,0] neg_lo:[0,1] neg_hi:[0,1]
	v_pk_add_f32 v[112:113], v[112:113], v[246:247] op_sel_hi:[1,0] neg_lo:[0,1] neg_hi:[0,1]
	v_pk_add_f32 v[114:115], v[114:115], v[246:247] op_sel_hi:[1,0] neg_lo:[0,1] neg_hi:[0,1]
	v_pk_add_f32 v[116:117], v[116:117], v[246:247] op_sel_hi:[1,0] neg_lo:[0,1] neg_hi:[0,1]
	v_pk_add_f32 v[118:119], v[118:119], v[246:247] op_sel_hi:[1,0] neg_lo:[0,1] neg_hi:[0,1]
	v_pk_add_f32 v[120:121], v[120:121], v[246:247] op_sel_hi:[1,0] neg_lo:[0,1] neg_hi:[0,1]
	v_pk_add_f32 v[122:123], v[122:123], v[246:247] op_sel_hi:[1,0] neg_lo:[0,1] neg_hi:[0,1]
	v_pk_add_f32 v[124:125], v[124:125], v[246:247] op_sel_hi:[1,0] neg_lo:[0,1] neg_hi:[0,1]
	v_pk_add_f32 v[126:127], v[126:127], v[246:247] op_sel_hi:[1,0] neg_lo:[0,1] neg_hi:[0,1]
	s_branch .Lf_even_exp
